# MLA loop: fold NaN-canonicalising v_max pairs, fill the post-S^T s_nop 8 with row-sum adds, running K/V stage bases + s_cselect_b64 for the stage DMA
# baseline (speedup 1.0000x reference)
.LBB0_857:
	v_lshl_add_u32 v200, s63, 8, v204
	v_ashrrev_i32_e32 v201, 31, v200
	v_mad_i64_i32 v[0:1], s[20:21], s58, v213, v[200:201]
	v_mad_u64_u32 v[2:3], s[20:21], v0, s51, v[188:189]
	v_mad_i32_i24 v3, v1, s51, v3
	global_load_dwordx4 v[144:147], v[2:3], off
	global_load_dwordx4 v[156:159], v[2:3], off offset:32
	global_load_dwordx4 v[168:171], v[2:3], off offset:64
	global_load_dwordx4 v[172:175], v[2:3], off offset:96
	global_load_dwordx4 v[164:167], v[2:3], off offset:128
	global_load_dwordx4 v[160:163], v[2:3], off offset:160
	global_load_dwordx4 v[152:155], v[2:3], off offset:192
	global_load_dwordx4 v[148:151], v[2:3], off offset:224
	global_load_dwordx4 v[140:143], v[2:3], off offset:256
	global_load_dwordx4 v[136:139], v[2:3], off offset:288
	global_load_dwordx4 v[132:135], v[2:3], off offset:320
	global_load_dwordx4 v[128:131], v[2:3], off offset:352
	s_mul_i32 s60, s58, 0x618000
	s_mul_hi_i32 s59, s58, 0x618000
	s_add_u32 s4, s3, s60
	s_mul_i32 s62, s58, 0x410000
	s_addc_u32 s5, s38, s59
	s_mul_hi_i32 s61, s58, 0x410000
	s_add_u32 s9, s39, s62
	s_addc_u32 s22, s40, s61
	s_and_b64 s[10:11], s[24:25], exec
	s_cselect_b32 s10, s9, s4
	s_cselect_b32 s11, s22, s5
	s_and_b64 s[12:13], s[26:27], exec
	s_cselect_b32 s12, s9, s4
	s_cselect_b32 s13, s22, s5
	s_and_b64 s[14:15], s[28:29], exec
	s_cselect_b32 s14, s9, s4
	s_cselect_b32 s15, s22, s5
	s_and_b64 s[16:17], s[30:31], exec
	s_cselect_b32 s16, s9, s4
	s_cselect_b32 s17, s22, s5
	s_and_b64 s[18:19], s[6:7], exec
	s_cselect_b32 s18, s9, s4
	s_cselect_b32 s19, s22, s5
	s_add_u32 s4, s4, 0x6000
	s_mov_b32 m0, s41
	s_addc_u32 s5, s5, 0
	v_lshl_add_u64 v[0:1], s[10:11], 0, v[190:191]
	s_add_u32 s9, s9, 0x80
	global_load_lds_dwordx4 v[0:1], off
	v_lshl_add_u64 v[0:1], s[12:13], 0, v[192:193]
	s_mov_b32 m0, s42
	s_addc_u32 s80, s22, 0
	global_load_lds_dwordx4 v[0:1], off
	v_lshl_add_u64 v[0:1], s[14:15], 0, v[194:195]
	s_mov_b32 m0, s43
	s_and_b64 s[20:21], s[24:25], exec
	global_load_lds_dwordx4 v[0:1], off
	v_lshl_add_u64 v[0:1], s[16:17], 0, v[196:197]
	s_mov_b32 m0, s44
	s_cselect_b32 s20, s9, s4
	s_cselect_b32 s21, s80, s5
	s_and_b64 s[22:23], s[26:27], exec
	global_load_lds_dwordx4 v[0:1], off
	v_lshl_add_u64 v[0:1], s[18:19], 0, v[198:199]
	s_mov_b32 m0, s45
	s_cselect_b32 s22, s9, s4
	s_cselect_b32 s23, s80, s5
	s_and_b64 s[74:75], s[28:29], exec
	global_load_lds_dwordx4 v[0:1], off
	v_lshl_add_u64 v[0:1], s[20:21], 0, v[190:191]
	s_mov_b32 m0, s46
	s_cselect_b32 s74, s9, s4
	s_cselect_b32 s75, s80, s5
	s_and_b64 s[76:77], s[30:31], exec
	global_load_lds_dwordx4 v[0:1], off
	v_lshl_add_u64 v[0:1], s[22:23], 0, v[192:193]
	s_mov_b32 m0, s47
	s_cselect_b32 s76, s9, s4
	s_cselect_b32 s77, s80, s5
	s_and_b64 s[78:79], s[6:7], exec
	global_load_lds_dwordx4 v[0:1], off
	v_lshl_add_u64 v[0:1], s[74:75], 0, v[194:195]
	s_mov_b32 m0, s48
	s_cselect_b32 s78, s9, s4
	s_cselect_b32 s79, s80, s5
	global_load_lds_dwordx4 v[0:1], off
	v_lshl_add_u64 v[0:1], s[76:77], 0, v[196:197]
	s_mov_b32 m0, s49
	v_cmp_lt_i32_e32 vcc, v223, v224
	global_load_lds_dwordx4 v[0:1], off
	v_lshl_add_u64 v[0:1], s[78:79], 0, v[198:199]
	s_mov_b32 m0, s50
	v_cndmask_b32_e32 v16, v222, v223, vcc
	global_load_lds_dwordx4 v[0:1], off
	s_waitcnt vmcnt(0)
	s_barrier
	ds_read_b128 v[0:3], v214
	ds_read_b128 v[4:7], v215
	s_waitcnt vmcnt(0) lgkmcnt(0)
	v_mfma_f32_32x32x16_bf16 v[66:81], v[0:3], v[144:147], 0
	v_lshlrev_b32_e32 v229, 2, v16
	s_mov_b32 s9, s8
	s_mov_b32 s10, s8
	s_mov_b32 s11, s8
	s_mov_b32 s12, s8
	s_mov_b32 s13, s8
	s_mov_b32 s14, s8
	v_mfma_f32_32x32x16_bf16 v[66:81], v[4:7], v[156:159], v[66:81]
	ds_read_b128 v[0:3], v216
	ds_read_b128 v[4:7], v217
	s_mov_b32 s15, s8
	s_mov_b32 s16, s8
	s_mov_b32 s17, s8
	s_mov_b32 s18, s8
	s_mov_b32 s19, s8
	s_mov_b32 s20, s8
	s_waitcnt lgkmcnt(1)
	v_mfma_f32_32x32x16_bf16 v[66:81], v[0:3], v[168:171], v[66:81]
	s_mov_b32 s21, s8
	s_mov_b32 s22, s8
	s_mov_b32 s23, s8
	s_cmp_eq_u32 s63, 0
	v_mov_b32_e32 v82, 0
	v_mov_b32_e32 v230, 0
	s_waitcnt lgkmcnt(0)
	v_mfma_f32_32x32x16_bf16 v[66:81], v[4:7], v[172:175], v[66:81]
	ds_read_b128 v[0:3], v218
	ds_read_b128 v[4:7], v219
	s_waitcnt lgkmcnt(1)
	v_mfma_f32_32x32x16_bf16 v[66:81], v[0:3], v[164:167], v[66:81]
	s_waitcnt lgkmcnt(0)
	v_mfma_f32_32x32x16_bf16 v[66:81], v[4:7], v[160:163], v[66:81]
	ds_read_b128 v[0:3], v220
	ds_read_b128 v[4:7], v221
	ds_read_b128 v[32:35], v212
	s_waitcnt lgkmcnt(2)
	v_mfma_f32_32x32x16_bf16 v[66:81], v[0:3], v[152:155], v[66:81]
	ds_read_b128 v[0:3], v206
	s_waitcnt lgkmcnt(2)
	v_mfma_f32_32x32x16_bf16 v[66:81], v[4:7], v[148:151], v[66:81]
	ds_read_b128 v[4:7], v208
	s_waitcnt lgkmcnt(1)
	v_mfma_f32_32x32x16_bf16 v[66:81], v[0:3], v[140:143], v[66:81]
	ds_read_b128 v[0:3], v210
	s_waitcnt lgkmcnt(1)
	v_mfma_f32_32x32x16_bf16 v[66:81], v[4:7], v[136:139], v[66:81]
	s_waitcnt lgkmcnt(0)
	v_mfma_f32_32x32x16_bf16 v[66:81], v[0:3], v[132:135], v[66:81]
	v_mov_b64_e32 v[0:1], s[8:9]
	v_mov_b64_e32 v[14:15], s[22:23]
	v_mov_b64_e32 v[2:3], s[10:11]
	v_mov_b64_e32 v[4:5], s[12:13]
	v_mov_b64_e32 v[6:7], s[14:15]
	v_mov_b64_e32 v[8:9], s[16:17]
	v_mov_b64_e32 v[10:11], s[18:19]
	v_mfma_f32_32x32x16_bf16 v[66:81], v[32:35], v[128:131], v[66:81]
	v_mov_b64_e32 v[12:13], s[20:21]
	v_mov_b64_e32 v[30:31], v[14:15]
	v_mov_b64_e32 v[62:63], v[14:15]
	v_mov_b64_e32 v[28:29], v[12:13]
	v_mov_b64_e32 v[26:27], v[10:11]
	v_mov_b64_e32 v[24:25], v[8:9]
	v_mov_b64_e32 v[22:23], v[6:7]
	s_nop 4
	v_max_f32_e32 v32, v67, v67
	v_max_f32_e32 v33, v66, v66
	v_max_f32_e32 v32, v33, v32
	v_max3_f32 v32, v32, v68, v69
	v_max3_f32 v32, v32, v70, v71
	v_max3_f32 v32, v32, v72, v73
	v_max3_f32 v32, v32, v74, v75
	v_max3_f32 v32, v32, v76, v77
	v_max3_f32 v32, v32, v78, v79
	v_max3_f32 v64, v32, v80, v81
	ds_bpermute_b32 v65, v229, v64
	v_mov_b64_e32 v[46:47], v[14:15]
	v_mov_b64_e32 v[20:21], v[4:5]
	v_mov_b64_e32 v[18:19], v[2:3]
	v_mov_b64_e32 v[16:17], v[0:1]
	s_waitcnt lgkmcnt(0)
	v_max_f32_e32 v65, v65, v65
	v_max_f32_e32 v65, v64, v65
	v_xor_b32_e32 v64, 0x80000000, v65
	v_mov_b64_e32 v[44:45], v[12:13]
	v_mov_b64_e32 v[42:43], v[10:11]
	v_mov_b64_e32 v[40:41], v[8:9]
	v_mov_b64_e32 v[38:39], v[6:7]
	v_mov_b64_e32 v[36:37], v[4:5]
	v_mov_b64_e32 v[34:35], v[2:3]
	v_mov_b64_e32 v[32:33], v[0:1]
	v_mov_b64_e32 v[60:61], v[12:13]
	v_mov_b64_e32 v[58:59], v[10:11]
	v_mov_b64_e32 v[56:57], v[8:9]
	v_mov_b64_e32 v[54:55], v[6:7]
	v_mov_b64_e32 v[52:53], v[4:5]
	v_mov_b64_e32 v[50:51], v[2:3]
	v_mov_b64_e32 v[48:49], v[0:1]
	s_cselect_b32 s9, 4, 0x104
	v_sub_f32_e32 v111, v81, v65
	v_sub_f32_e32 v110, v80, v65
	v_sub_f32_e32 v109, v79, v65
	v_sub_f32_e32 v108, v78, v65
	v_sub_f32_e32 v107, v77, v65
	v_sub_f32_e32 v106, v76, v65
	v_sub_f32_e32 v105, v75, v65
	v_sub_f32_e32 v104, v74, v65
	v_sub_f32_e32 v103, v73, v65
	v_sub_f32_e32 v102, v72, v65
	v_sub_f32_e32 v101, v71, v65
	v_sub_f32_e32 v100, v70, v65
	v_sub_f32_e32 v99, v69, v65
	v_sub_f32_e32 v98, v68, v65
	v_sub_f32_e32 v97, v67, v65
	v_sub_f32_e32 v96, v66, v65
	v_mov_b32_e32 v65, v64
	v_mov_b32_e32 v66, v64
	v_mov_b32_e32 v67, v64
	v_mov_b32_e32 v68, v64
	v_mov_b32_e32 v69, v64
	v_mov_b32_e32 v70, v64
	v_mov_b32_e32 v71, v64
	v_mov_b32_e32 v72, v64
	v_mov_b32_e32 v73, v64
	v_mov_b32_e32 v74, v64
	v_mov_b32_e32 v75, v64
	v_mov_b32_e32 v76, v64
	v_mov_b32_e32 v77, v64
	v_mov_b32_e32 v78, v64
	v_mov_b32_e32 v79, v64
	s_add_u32 s98, s34, s60
	s_addc_u32 s99, s35, s59
	s_add_u32 s98, s98, 0x140fc000
	s_addc_u32 s99, s99, 0
	s_add_u32 s100, s34, s62
	s_addc_u32 s101, s35, s61
	s_add_u32 s100, s100, 0x171b0100
	s_addc_u32 s101, s101, 0
	v_cmp_lt_f32_e32 vcc, 0, v82
	s_cbranch_vccz .LBB0_859

.LBB0_859:
	ds_read_b128 v[236:239], v214 offset:8192
	ds_read_b128 v[240:243], v215 offset:8192
	ds_read_b128 v[244:247], v216 offset:8192
	ds_read_b128 v[248:251], v217 offset:8192
	ds_read_b128 v[252:255], v218 offset:8192
	ds_read_b128 v[176:179], v219 offset:8192
	v_exp_f32_e32 v97, v97
	v_exp_f32_e32 v99, v99
	v_exp_f32_e32 v100, v100
	v_exp_f32_e32 v101, v101
	v_exp_f32_e32 v102, v102
	v_exp_f32_e32 v103, v103
	v_exp_f32_e32 v106, v106
	v_exp_f32_e32 v107, v107
	s_waitcnt lgkmcnt(3)
	v_mfma_f32_32x32x16_bf16 v[80:95], v[236:239], v[144:147], v[64:79]
	ds_read_b128 v[180:183], v220 offset:8192
	v_exp_f32_e32 v108, v108
	v_exp_f32_e32 v109, v109
	v_exp_f32_e32 v110, v110
	v_exp_f32_e32 v111, v111
	v_mfma_f32_32x32x16_bf16 v[80:95], v[240:243], v[156:159], v[80:95]
	ds_read_b128 v[236:239], v221 offset:8192
	s_mov_b32 m0, s52
	s_cmp_lg_u64 s[24:25], 0
	s_cselect_b64 s[4:5], s[100:101], s[98:99]
	global_load_lds_dwordx4 v190, s[4:5]
	s_mov_b32 m0, s53
	s_cmp_lg_u64 s[26:27], 0
	s_cselect_b64 s[4:5], s[100:101], s[98:99]
	global_load_lds_dwordx4 v192, s[4:5]
	s_mov_b32 m0, s54
	s_cmp_lg_u64 s[28:29], 0
	s_cselect_b64 s[4:5], s[100:101], s[98:99]
	global_load_lds_dwordx4 v194, s[4:5]
	s_mov_b32 m0, s55
	s_cmp_lg_u64 s[30:31], 0
	s_cselect_b64 s[4:5], s[100:101], s[98:99]
	global_load_lds_dwordx4 v196, s[4:5]
	s_mov_b32 m0, s56
	s_cmp_lg_u64 s[6:7], 0
	s_cselect_b64 s[4:5], s[100:101], s[98:99]
	global_load_lds_dwordx4 v198, s[4:5]
	s_add_u32 s98, s98, 0x6000
	s_addc_u32 s99, s99, 0
	s_add_u32 s100, s100, 0x80
	s_addc_u32 s101, s101, 0
	v_mfma_f32_32x32x16_bf16 v[80:95], v[244:247], v[168:171], v[80:95]
	ds_read_b128 v[240:243], v205 offset:53248
	s_waitcnt lgkmcnt(3)
	v_mfma_f32_32x32x16_bf16 v[80:95], v[248:251], v[172:175], v[80:95]
	ds_read_b128 v[244:247], v207 offset:53248
	v_mfma_f32_32x32x16_bf16 v[80:95], v[252:255], v[164:167], v[80:95]
	ds_read_b128 v[248:251], v209 offset:53248
	v_mfma_f32_32x32x16_bf16 v[80:95], v[176:179], v[160:163], v[80:95]
	ds_read_b128 v[252:255], v211 offset:53248
	s_waitcnt lgkmcnt(3)
	v_mfma_f32_32x32x16_bf16 v[80:95], v[180:183], v[152:155], v[80:95]
	ds_read_b128 v[176:179], v225
	v_mfma_f32_32x32x16_bf16 v[80:95], v[236:239], v[148:151], v[80:95]
	ds_read_b128 v[180:183], v225 offset:4096
	v_mfma_f32_32x32x16_bf16 v[80:95], v[240:243], v[140:143], v[80:95]
	ds_read_b128 v[236:239], v225 offset:8192
	s_waitcnt lgkmcnt(3)
	v_mfma_f32_32x32x16_bf16 v[80:95], v[244:247], v[136:139], v[80:95]
	ds_read_b128 v[240:243], v225 offset:12288
	v_mfma_f32_32x32x16_bf16 v[80:95], v[248:251], v[132:135], v[80:95]
	ds_read_b128 v[244:247], v226
	v_mfma_f32_32x32x16_bf16 v[80:95], v[252:255], v[128:131], v[80:95]
	ds_read_b128 v[248:251], v226 offset:4096
	v_exp_f32_e32 v112, v96
	v_exp_f32_e32 v113, v98
	v_exp_f32_e32 v114, v104
	v_exp_f32_e32 v115, v105
	v_add_f32_e32 v96, 0, v112
	v_add_f32_e32 v96, v97, v96
	v_add_f32_e32 v96, v113, v96
	v_add_f32_e32 v96, v99, v96
	v_add_f32_e32 v96, v100, v96
	v_add_f32_e32 v96, v101, v96
	v_add_f32_e32 v96, v102, v96
	v_add_f32_e32 v96, v103, v96
	v_cvt_pk_bf16_f32 v100, v100, v101
	v_cvt_pk_bf16_f32 v101, v102, v103
	v_cvt_pk_bf16_f32 v98, v112, v97
	v_cvt_pk_bf16_f32 v99, v113, v99
	v_add_f32_e32 v96, v114, v96
	s_waitcnt lgkmcnt(3)
	v_mfma_f32_32x32x16_bf16 v[48:63], v[176:179], v[98:101], v[48:63]
	ds_read_b128 v[252:255], v226 offset:8192
	v_add_f32_e32 v96, v115, v96
	v_add_f32_e32 v96, v106, v96
	v_add_f32_e32 v96, v107, v96
	v_add_f32_e32 v96, v108, v96
	v_add_f32_e32 v96, v109, v96
	v_add_f32_e32 v96, v110, v96
	v_mfma_f32_32x32x16_bf16 v[32:47], v[180:183], v[98:101], v[32:47]
	ds_read_b128 v[176:179], v226 offset:12288
	v_add_f32_e32 v96, v111, v96
	v_add_f32_e32 v112, v230, v96
	v_mfma_f32_32x32x16_bf16 v[16:31], v[236:239], v[98:101], v[16:31]
	ds_read_b128 v[180:183], v214 offset:16384
	s_waitcnt lgkmcnt(3)
	v_mfma_f32_32x32x16_bf16 v[0:15], v[240:243], v[98:101], v[0:15]
	ds_read_b128 v[236:239], v215 offset:16384
	v_cvt_pk_bf16_f32 v98, v114, v115
	v_cvt_pk_bf16_f32 v99, v106, v107
	v_cvt_pk_bf16_f32 v100, v108, v109
	v_cvt_pk_bf16_f32 v101, v110, v111
	s_nop 0
	s_nop 0
	v_mfma_f32_32x32x16_bf16 v[48:63], v[244:247], v[98:101], v[48:63]
	ds_read_b128 v[240:243], v216 offset:16384
	v_mfma_f32_32x32x16_bf16 v[32:47], v[248:251], v[98:101], v[32:47]
	ds_read_b128 v[244:247], v217 offset:16384
	s_waitcnt lgkmcnt(3)
	v_mfma_f32_32x32x16_bf16 v[16:31], v[252:255], v[98:101], v[16:31]
	ds_read_b128 v[248:251], v218 offset:16384
	v_mfma_f32_32x32x16_bf16 v[0:15], v[176:179], v[98:101], v[0:15]
	ds_read_b128 v[252:255], v219 offset:16384
	v_max_f32_e32 v97, v80, v81
	v_max3_f32 v97, v97, v82, v83
	v_max3_f32 v97, v97, v84, v85
	v_max3_f32 v97, v97, v86, v87
	v_max3_f32 v97, v97, v88, v89
	v_max3_f32 v97, v97, v90, v91
	v_max3_f32 v97, v97, v92, v93
	v_max3_f32 v97, v97, v94, v95
	ds_bpermute_b32 v98, v229, v97
	s_waitcnt lgkmcnt(0)
	v_max_f32_e32 v96, v97, v98
	v_cmp_lt_f32_e32 vcc, 0, v96
	s_cbranch_vccz .LBB0_861
	v_max_f32_e32 v96, v96, v96
	v_max_f32_e32 v96, 0, v96
	v_exp_f32_e64 v98, -v96
	v_pk_add_f32 v[80:81], v[80:81], v[96:97] op_sel_hi:[1,0] neg_lo:[0,1] neg_hi:[0,1]
	v_pk_add_f32 v[82:83], v[82:83], v[96:97] op_sel_hi:[1,0] neg_lo:[0,1] neg_hi:[0,1]
	v_pk_add_f32 v[84:85], v[84:85], v[96:97] op_sel_hi:[1,0] neg_lo:[0,1] neg_hi:[0,1]
	v_mul_f32_e32 v112, v112, v98
	v_pk_add_f32 v[86:87], v[86:87], v[96:97] op_sel_hi:[1,0] neg_lo:[0,1] neg_hi:[0,1]
	v_pk_add_f32 v[88:89], v[88:89], v[96:97] op_sel_hi:[1,0] neg_lo:[0,1] neg_hi:[0,1]
	v_pk_add_f32 v[90:91], v[90:91], v[96:97] op_sel_hi:[1,0] neg_lo:[0,1] neg_hi:[0,1]
	v_pk_add_f32 v[92:93], v[92:93], v[96:97] op_sel_hi:[1,0] neg_lo:[0,1] neg_hi:[0,1]
	v_sub_f32_e32 v79, v79, v96
	v_sub_f32_e32 v78, v78, v96
	v_sub_f32_e32 v77, v77, v96
	v_sub_f32_e32 v76, v76, v96
	v_sub_f32_e32 v75, v75, v96
	v_sub_f32_e32 v74, v74, v96
	v_sub_f32_e32 v73, v73, v96
	v_sub_f32_e32 v72, v72, v96
	v_sub_f32_e32 v71, v71, v96
	v_sub_f32_e32 v70, v70, v96
	v_sub_f32_e32 v69, v69, v96
	v_sub_f32_e32 v68, v68, v96
	v_sub_f32_e32 v67, v67, v96
	v_sub_f32_e32 v66, v66, v96
	v_sub_f32_e32 v65, v65, v96
	v_sub_f32_e32 v64, v64, v96
	v_pk_add_f32 v[94:95], v[94:95], v[96:97] op_sel_hi:[1,0] neg_lo:[0,1] neg_hi:[0,1]
	v_pk_mul_f32 v[62:63], v[62:63], v[98:99] op_sel_hi:[1,0]
	v_pk_mul_f32 v[60:61], v[60:61], v[98:99] op_sel_hi:[1,0]
	v_pk_mul_f32 v[58:59], v[58:59], v[98:99] op_sel_hi:[1,0]
	v_pk_mul_f32 v[56:57], v[56:57], v[98:99] op_sel_hi:[1,0]
	v_pk_mul_f32 v[54:55], v[54:55], v[98:99] op_sel_hi:[1,0]
	v_pk_mul_f32 v[52:53], v[52:53], v[98:99] op_sel_hi:[1,0]
	v_pk_mul_f32 v[50:51], v[50:51], v[98:99] op_sel_hi:[1,0]
	v_pk_mul_f32 v[48:49], v[48:49], v[98:99] op_sel_hi:[1,0]
	v_pk_mul_f32 v[46:47], v[46:47], v[98:99] op_sel_hi:[1,0]
	v_pk_mul_f32 v[44:45], v[44:45], v[98:99] op_sel_hi:[1,0]
	v_pk_mul_f32 v[42:43], v[42:43], v[98:99] op_sel_hi:[1,0]
	v_pk_mul_f32 v[40:41], v[40:41], v[98:99] op_sel_hi:[1,0]
	v_pk_mul_f32 v[38:39], v[38:39], v[98:99] op_sel_hi:[1,0]
	v_pk_mul_f32 v[36:37], v[36:37], v[98:99] op_sel_hi:[1,0]
	v_pk_mul_f32 v[34:35], v[34:35], v[98:99] op_sel_hi:[1,0]
	v_pk_mul_f32 v[32:33], v[32:33], v[98:99] op_sel_hi:[1,0]
	v_pk_mul_f32 v[30:31], v[30:31], v[98:99] op_sel_hi:[1,0]
	v_pk_mul_f32 v[28:29], v[28:29], v[98:99] op_sel_hi:[1,0]
	v_pk_mul_f32 v[26:27], v[26:27], v[98:99] op_sel_hi:[1,0]
	v_pk_mul_f32 v[24:25], v[24:25], v[98:99] op_sel_hi:[1,0]
	v_pk_mul_f32 v[22:23], v[22:23], v[98:99] op_sel_hi:[1,0]
	v_pk_mul_f32 v[20:21], v[20:21], v[98:99] op_sel_hi:[1,0]
	v_pk_mul_f32 v[18:19], v[18:19], v[98:99] op_sel_hi:[1,0]
	v_pk_mul_f32 v[16:17], v[16:17], v[98:99] op_sel_hi:[1,0]
	v_pk_mul_f32 v[14:15], v[14:15], v[98:99] op_sel_hi:[1,0]
	v_pk_mul_f32 v[12:13], v[12:13], v[98:99] op_sel_hi:[1,0]
	v_pk_mul_f32 v[10:11], v[10:11], v[98:99] op_sel_hi:[1,0]
	v_pk_mul_f32 v[8:9], v[8:9], v[98:99] op_sel_hi:[1,0]
	v_pk_mul_f32 v[6:7], v[6:7], v[98:99] op_sel_hi:[1,0]
	v_pk_mul_f32 v[4:5], v[4:5], v[98:99] op_sel_hi:[1,0]
	v_pk_mul_f32 v[2:3], v[2:3], v[98:99] op_sel_hi:[1,0]
	v_pk_mul_f32 v[0:1], v[0:1], v[98:99] op_sel_hi:[1,0]
.LBB0_861:
	v_exp_f32_e32 v113, v80
	v_exp_f32_e32 v122, v81
	v_exp_f32_e32 v123, v82
	v_mfma_f32_32x32x16_bf16 v[96:111], v[180:183], v[144:147], v[64:79]
	ds_read_b128 v[176:179], v220 offset:16384
	v_exp_f32_e32 v124, v83
	v_exp_f32_e32 v125, v84
	v_exp_f32_e32 v126, v85
	v_exp_f32_e32 v127, v86
	v_exp_f32_e32 v230, v87
	v_exp_f32_e32 v88, v88
	v_exp_f32_e32 v89, v89
	v_mfma_f32_32x32x16_bf16 v[96:111], v[236:239], v[156:159], v[96:111]
	ds_read_b128 v[180:183], v221 offset:16384
	v_exp_f32_e32 v90, v90
	v_exp_f32_e32 v91, v91
	v_exp_f32_e32 v92, v92
	v_exp_f32_e32 v93, v93
	v_exp_f32_e32 v94, v94
	v_exp_f32_e32 v95, v95
	v_mfma_f32_32x32x16_bf16 v[96:111], v[240:243], v[168:171], v[96:111]
	ds_read_b128 v[236:239], v205 offset:57344
	v_mfma_f32_32x32x16_bf16 v[96:111], v[244:247], v[172:175], v[96:111]
	ds_read_b128 v[240:243], v207 offset:57344
	v_mfma_f32_32x32x16_bf16 v[96:111], v[248:251], v[164:167], v[96:111]
	ds_read_b128 v[244:247], v209 offset:57344
	v_mfma_f32_32x32x16_bf16 v[96:111], v[252:255], v[160:163], v[96:111]
	ds_read_b128 v[248:251], v211 offset:57344
	s_waitcnt lgkmcnt(3)
	v_mfma_f32_32x32x16_bf16 v[96:111], v[176:179], v[152:155], v[96:111]
	ds_read_b128 v[252:255], v227
	v_mfma_f32_32x32x16_bf16 v[96:111], v[180:183], v[148:151], v[96:111]
	ds_read_b128 v[176:179], v227 offset:4096
	v_mfma_f32_32x32x16_bf16 v[96:111], v[236:239], v[140:143], v[96:111]
	ds_read_b128 v[180:183], v227 offset:8192
	s_waitcnt lgkmcnt(3)
	v_mfma_f32_32x32x16_bf16 v[96:111], v[240:243], v[136:139], v[96:111]
	ds_read_b128 v[236:239], v227 offset:12288
	v_mfma_f32_32x32x16_bf16 v[96:111], v[244:247], v[132:135], v[96:111]
	ds_read_b128 v[240:243], v228 offset:4096
	v_cvt_pk_bf16_f32 v114, v113, v122
	v_cvt_pk_bf16_f32 v115, v123, v124
	v_cvt_pk_bf16_f32 v116, v125, v126
	v_cvt_pk_bf16_f32 v117, v127, v230
	v_mfma_f32_32x32x16_bf16 v[96:111], v[248:251], v[128:131], v[96:111]
	ds_read_b128 v[244:247], v228
	v_add_f32_e32 v118, 0, v113
	v_add_f32_e32 v113, v122, v118
	v_add_f32_e32 v113, v123, v113
	s_waitcnt lgkmcnt(3)
	v_mfma_f32_32x32x16_bf16 v[48:63], v[252:255], v[114:117], v[48:63]
	ds_read_b128 v[248:251], v228 offset:8192
	v_add_f32_e32 v80, v124, v113
	v_add_f32_e32 v80, v125, v80
	v_add_f32_e32 v80, v126, v80
	v_add_f32_e32 v113, v127, v80
	v_mfma_f32_32x32x16_bf16 v[32:47], v[176:179], v[114:117], v[32:47]
	ds_read_b128 v[252:255], v228 offset:12288
	v_add_f32_e32 v84, v230, v113
	v_add_f32_e32 v84, v88, v84
	v_add_f32_e32 v113, v89, v84
	v_mfma_f32_32x32x16_bf16 v[16:31], v[180:183], v[114:117], v[16:31]
	ds_read_b128 v[176:179], v214 offset:24576
	v_add_f32_e32 v80, v90, v113
	v_add_f32_e32 v80, v91, v80
	v_add_f32_e32 v80, v92, v80
	v_add_f32_e32 v113, v93, v80
	v_add_f32_e32 v113, v94, v113
	s_waitcnt lgkmcnt(3)
	v_mfma_f32_32x32x16_bf16 v[0:15], v[236:239], v[114:117], v[0:15]
	ds_read_b128 v[180:183], v215 offset:24576
	v_cvt_pk_bf16_f32 v84, v88, v89
	v_cvt_pk_bf16_f32 v85, v90, v91
	v_cvt_pk_bf16_f32 v86, v92, v93
	v_max_f32_e32 v92, v96, v97
	v_max3_f32 v92, v92, v98, v99
	v_max3_f32 v92, v92, v100, v101
	v_cvt_pk_bf16_f32 v87, v94, v95
	v_max3_f32 v92, v92, v102, v103
	v_add_f32_e32 v94, v95, v113
	v_mfma_f32_32x32x16_bf16 v[32:47], v[240:243], v[84:87], v[32:47]
	ds_read_b128 v[236:239], v216 offset:24576
	v_max3_f32 v88, v92, v104, v105
	v_max3_f32 v88, v88, v106, v107
	v_max3_f32 v88, v88, v108, v109
	v_max3_f32 v92, v88, v110, v111
	ds_bpermute_b32 v93, v229, v92
	v_add_f32_e32 v112, v112, v94
	v_mfma_f32_32x32x16_bf16 v[48:63], v[244:247], v[84:87], v[48:63]
	ds_read_b128 v[240:243], v217 offset:24576
	s_waitcnt vmcnt(0)
	s_barrier
	s_waitcnt lgkmcnt(4)
	v_mfma_f32_32x32x16_bf16 v[16:31], v[248:251], v[84:87], v[16:31]
	ds_read_b128 v[244:247], v218 offset:24576
	s_waitcnt lgkmcnt(2)
	v_max_f32_e32 v80, v92, v93
	v_cmp_lt_f32_e32 vcc, 0, v80
	v_mfma_f32_32x32x16_bf16 v[0:15], v[252:255], v[84:87], v[0:15]
	ds_read_b128 v[248:251], v219 offset:24576
	s_cbranch_vccz .LBB0_863
	v_max_f32_e32 v80, v80, v80
	v_max_f32_e32 v80, 0, v80
	v_exp_f32_e64 v82, -v80
	v_pk_add_f32 v[96:97], v[96:97], v[80:81] op_sel_hi:[1,0] neg_lo:[0,1] neg_hi:[0,1]
	v_pk_add_f32 v[98:99], v[98:99], v[80:81] op_sel_hi:[1,0] neg_lo:[0,1] neg_hi:[0,1]
	v_pk_add_f32 v[100:101], v[100:101], v[80:81] op_sel_hi:[1,0] neg_lo:[0,1] neg_hi:[0,1]
	v_mul_f32_e32 v112, v112, v82
	v_pk_add_f32 v[102:103], v[102:103], v[80:81] op_sel_hi:[1,0] neg_lo:[0,1] neg_hi:[0,1]
	v_pk_add_f32 v[104:105], v[104:105], v[80:81] op_sel_hi:[1,0] neg_lo:[0,1] neg_hi:[0,1]
	v_pk_add_f32 v[106:107], v[106:107], v[80:81] op_sel_hi:[1,0] neg_lo:[0,1] neg_hi:[0,1]
	v_pk_add_f32 v[108:109], v[108:109], v[80:81] op_sel_hi:[1,0] neg_lo:[0,1] neg_hi:[0,1]
	v_sub_f32_e32 v79, v79, v80
	v_sub_f32_e32 v78, v78, v80
	v_sub_f32_e32 v77, v77, v80
	v_sub_f32_e32 v76, v76, v80
	v_sub_f32_e32 v75, v75, v80
	v_sub_f32_e32 v74, v74, v80
	v_sub_f32_e32 v73, v73, v80
	v_sub_f32_e32 v72, v72, v80
	v_sub_f32_e32 v71, v71, v80
	v_sub_f32_e32 v70, v70, v80
	v_sub_f32_e32 v69, v69, v80
	v_sub_f32_e32 v68, v68, v80
	v_sub_f32_e32 v67, v67, v80
	v_sub_f32_e32 v66, v66, v80
	v_sub_f32_e32 v65, v65, v80
	v_sub_f32_e32 v64, v64, v80
	v_pk_add_f32 v[110:111], v[110:111], v[80:81] op_sel_hi:[1,0] neg_lo:[0,1] neg_hi:[0,1]
	v_pk_mul_f32 v[62:63], v[62:63], v[82:83] op_sel_hi:[1,0]
	v_pk_mul_f32 v[60:61], v[60:61], v[82:83] op_sel_hi:[1,0]
	v_pk_mul_f32 v[58:59], v[58:59], v[82:83] op_sel_hi:[1,0]
	v_pk_mul_f32 v[56:57], v[56:57], v[82:83] op_sel_hi:[1,0]
	v_pk_mul_f32 v[54:55], v[54:55], v[82:83] op_sel_hi:[1,0]
	v_pk_mul_f32 v[52:53], v[52:53], v[82:83] op_sel_hi:[1,0]
	v_pk_mul_f32 v[50:51], v[50:51], v[82:83] op_sel_hi:[1,0]
	v_pk_mul_f32 v[48:49], v[48:49], v[82:83] op_sel_hi:[1,0]
	v_pk_mul_f32 v[46:47], v[46:47], v[82:83] op_sel_hi:[1,0]
	v_pk_mul_f32 v[44:45], v[44:45], v[82:83] op_sel_hi:[1,0]
	v_pk_mul_f32 v[42:43], v[42:43], v[82:83] op_sel_hi:[1,0]
	v_pk_mul_f32 v[40:41], v[40:41], v[82:83] op_sel_hi:[1,0]
	v_pk_mul_f32 v[38:39], v[38:39], v[82:83] op_sel_hi:[1,0]
	v_pk_mul_f32 v[36:37], v[36:37], v[82:83] op_sel_hi:[1,0]
	v_pk_mul_f32 v[34:35], v[34:35], v[82:83] op_sel_hi:[1,0]
	v_pk_mul_f32 v[32:33], v[32:33], v[82:83] op_sel_hi:[1,0]
	v_pk_mul_f32 v[30:31], v[30:31], v[82:83] op_sel_hi:[1,0]
	v_pk_mul_f32 v[28:29], v[28:29], v[82:83] op_sel_hi:[1,0]
	v_pk_mul_f32 v[26:27], v[26:27], v[82:83] op_sel_hi:[1,0]
	v_pk_mul_f32 v[24:25], v[24:25], v[82:83] op_sel_hi:[1,0]
	v_pk_mul_f32 v[22:23], v[22:23], v[82:83] op_sel_hi:[1,0]
	v_pk_mul_f32 v[20:21], v[20:21], v[82:83] op_sel_hi:[1,0]
	v_pk_mul_f32 v[18:19], v[18:19], v[82:83] op_sel_hi:[1,0]
	v_pk_mul_f32 v[16:17], v[16:17], v[82:83] op_sel_hi:[1,0]
	v_pk_mul_f32 v[14:15], v[14:15], v[82:83] op_sel_hi:[1,0]
	v_pk_mul_f32 v[12:13], v[12:13], v[82:83] op_sel_hi:[1,0]
	v_pk_mul_f32 v[10:11], v[10:11], v[82:83] op_sel_hi:[1,0]
	v_pk_mul_f32 v[8:9], v[8:9], v[82:83] op_sel_hi:[1,0]
	v_pk_mul_f32 v[6:7], v[6:7], v[82:83] op_sel_hi:[1,0]
	v_pk_mul_f32 v[4:5], v[4:5], v[82:83] op_sel_hi:[1,0]
	v_pk_mul_f32 v[2:3], v[2:3], v[82:83] op_sel_hi:[1,0]
	v_pk_mul_f32 v[0:1], v[0:1], v[82:83] op_sel_hi:[1,0]
.LBB0_863:
	v_exp_f32_e32 v96, v96
	v_exp_f32_e32 v97, v97
	v_exp_f32_e32 v98, v98
	v_mfma_f32_32x32x16_bf16 v[80:95], v[176:179], v[144:147], v[64:79]
	ds_read_b128 v[252:255], v220 offset:24576
	v_exp_f32_e32 v99, v99
	v_exp_f32_e32 v100, v100
	v_exp_f32_e32 v101, v101
	v_exp_f32_e32 v102, v102
	v_exp_f32_e32 v103, v103
	v_cvt_pk_bf16_f32 v122, v96, v97
	v_cvt_pk_bf16_f32 v123, v98, v99
	v_mfma_f32_32x32x16_bf16 v[80:95], v[180:183], v[156:159], v[80:95]
	ds_read_b128 v[176:179], v221 offset:24576
	s_add_i32 s4, s8, 3
	s_cmp_ge_u32 s4, s9
	s_cbranch_scc1 .Lmla_dma_skip_t1
	s_mov_b32 m0, s41
	s_cmp_lg_u64 s[24:25], 0
	s_cselect_b64 s[4:5], s[100:101], s[98:99]
	global_load_lds_dwordx4 v190, s[4:5]
	s_mov_b32 m0, s42
	s_cmp_lg_u64 s[26:27], 0
	s_cselect_b64 s[4:5], s[100:101], s[98:99]
	global_load_lds_dwordx4 v192, s[4:5]
	s_mov_b32 m0, s43
	s_cmp_lg_u64 s[28:29], 0
	s_cselect_b64 s[4:5], s[100:101], s[98:99]
	global_load_lds_dwordx4 v194, s[4:5]
	s_mov_b32 m0, s44
	s_cmp_lg_u64 s[30:31], 0
	s_cselect_b64 s[4:5], s[100:101], s[98:99]
	global_load_lds_dwordx4 v196, s[4:5]
	s_mov_b32 m0, s45
	s_cmp_lg_u64 s[6:7], 0
	s_cselect_b64 s[4:5], s[100:101], s[98:99]
	global_load_lds_dwordx4 v198, s[4:5]
	s_add_u32 s98, s98, 0x6000
	s_addc_u32 s99, s99, 0
	s_add_u32 s100, s100, 0x80
	s_addc_u32 s101, s101, 0
.Lmla_dma_skip_t1:
	v_cvt_pk_bf16_f32 v124, v100, v101
	v_cvt_pk_bf16_f32 v125, v102, v103
	v_exp_f32_e32 v104, v104
	v_exp_f32_e32 v105, v105
	v_exp_f32_e32 v106, v106
	v_exp_f32_e32 v107, v107
	v_mfma_f32_32x32x16_bf16 v[80:95], v[236:239], v[168:171], v[80:95]
	ds_read_b128 v[180:183], v205 offset:61440
	v_exp_f32_e32 v108, v108
	v_exp_f32_e32 v109, v109
	v_exp_f32_e32 v110, v110
	v_exp_f32_e32 v111, v111
	s_add_i32 s16, s8, 3
	s_cmp_lt_u32 s16, s9
	s_cselect_b64 s[10:11], -1, 0
	s_waitcnt lgkmcnt(3)
	v_mfma_f32_32x32x16_bf16 v[80:95], v[240:243], v[172:175], v[80:95]
	ds_read_b128 v[236:239], v207 offset:61440
	s_cmp_ge_u32 s16, s9
	v_mfma_f32_32x32x16_bf16 v[80:95], v[244:247], v[164:167], v[80:95]
	ds_read_b128 v[240:243], v209 offset:61440
	v_mfma_f32_32x32x16_bf16 v[80:95], v[248:251], v[160:163], v[80:95]
	ds_read_b128 v[244:247], v211 offset:61440
	s_waitcnt lgkmcnt(3)
	v_mfma_f32_32x32x16_bf16 v[80:95], v[252:255], v[152:155], v[80:95]
	ds_read_b128 v[248:251], v225 offset:16384
	v_mfma_f32_32x32x16_bf16 v[80:95], v[176:179], v[148:151], v[80:95]
	ds_read_b128 v[252:255], v225 offset:20480
	v_mfma_f32_32x32x16_bf16 v[80:95], v[180:183], v[140:143], v[80:95]
	ds_read_b128 v[176:179], v225 offset:24576
	s_waitcnt lgkmcnt(3)
	v_mfma_f32_32x32x16_bf16 v[80:95], v[236:239], v[136:139], v[80:95]
	ds_read_b128 v[180:183], v225 offset:28672
	v_mfma_f32_32x32x16_bf16 v[80:95], v[240:243], v[132:135], v[80:95]
	ds_read_b128 v[236:239], v226 offset:16384
	v_mfma_f32_32x32x16_bf16 v[80:95], v[244:247], v[128:131], v[80:95]
	ds_read_b128 v[240:243], v226 offset:20480
	s_waitcnt lgkmcnt(3)
	v_mfma_f32_32x32x16_bf16 v[48:63], v[248:251], v[122:125], v[48:63]
	ds_read_b128 v[244:247], v226 offset:24576
	v_add_f32_e32 v96, 0, v96
	v_add_f32_e32 v96, v97, v96
	v_add_f32_e32 v96, v98, v96
	v_add_f32_e32 v96, v99, v96
	v_add_f32_e32 v96, v100, v96
	v_add_f32_e32 v96, v101, v96
	v_add_f32_e32 v96, v102, v96
	v_add_f32_e32 v96, v103, v96
	v_add_f32_e32 v96, v104, v96
	v_max_f32_e32 v113, v80, v81
	v_max3_f32 v113, v113, v82, v83
	v_max3_f32 v113, v113, v84, v85
	v_max3_f32 v113, v113, v86, v87
	v_max3_f32 v113, v113, v88, v89
	v_mfma_f32_32x32x16_bf16 v[32:47], v[252:255], v[122:125], v[32:47]
	ds_read_b128 v[248:251], v226 offset:28672
	v_max3_f32 v113, v113, v90, v91
	v_max3_f32 v113, v113, v92, v93
	v_max3_f32 v113, v113, v94, v95
	v_mfma_f32_32x32x16_bf16 v[16:31], v[176:179], v[122:125], v[16:31]
	ds_read_b128 v[252:255], v214 offset:32768
	s_waitcnt lgkmcnt(3)
	v_mfma_f32_32x32x16_bf16 v[0:15], v[180:183], v[122:125], v[0:15]
	ds_read_b128 v[176:179], v215 offset:32768
	v_cvt_pk_bf16_f32 v118, v104, v105
	v_cvt_pk_bf16_f32 v119, v106, v107
	v_cvt_pk_bf16_f32 v120, v108, v109
	v_cvt_pk_bf16_f32 v121, v110, v111
	s_nop 0
	s_nop 0
	v_mfma_f32_32x32x16_bf16 v[48:63], v[236:239], v[118:121], v[48:63]
	ds_read_b128 v[180:183], v216 offset:32768
	v_mfma_f32_32x32x16_bf16 v[32:47], v[240:243], v[118:121], v[32:47]
	ds_read_b128 v[236:239], v217 offset:32768
	s_waitcnt lgkmcnt(3)
	v_mfma_f32_32x32x16_bf16 v[16:31], v[244:247], v[118:121], v[16:31]
	ds_read_b128 v[240:243], v218 offset:32768
	ds_bpermute_b32 v114, v229, v113
	v_mfma_f32_32x32x16_bf16 v[0:15], v[248:251], v[118:121], v[0:15]
	ds_read_b128 v[244:247], v219 offset:32768
.LBB0_865:
	v_add_f32_e32 v96, v105, v96
	v_add_f32_e32 v96, v106, v96
	v_add_f32_e32 v96, v107, v96
	v_add_f32_e32 v96, v108, v96
	v_add_f32_e32 v96, v109, v96
	v_add_f32_e32 v96, v110, v96
	v_add_f32_e32 v96, v111, v96
	v_add_f32_e32 v112, v112, v96
	v_max_f32_e32 v97, v113, v113
	s_waitcnt lgkmcnt(1)
	v_max_f32_e32 v96, v97, v114
	v_cmp_lt_f32_e32 vcc, 0, v96
	s_cbranch_vccz .LBB0_867
	v_max_f32_e32 v96, v96, v96
	v_max_f32_e32 v96, 0, v96
	v_exp_f32_e64 v98, -v96
	v_pk_add_f32 v[80:81], v[80:81], v[96:97] op_sel_hi:[1,0] neg_lo:[0,1] neg_hi:[0,1]
	v_pk_add_f32 v[82:83], v[82:83], v[96:97] op_sel_hi:[1,0] neg_lo:[0,1] neg_hi:[0,1]
	v_pk_add_f32 v[84:85], v[84:85], v[96:97] op_sel_hi:[1,0] neg_lo:[0,1] neg_hi:[0,1]
	v_mul_f32_e32 v112, v112, v98
	v_pk_add_f32 v[86:87], v[86:87], v[96:97] op_sel_hi:[1,0] neg_lo:[0,1] neg_hi:[0,1]
	v_pk_add_f32 v[88:89], v[88:89], v[96:97] op_sel_hi:[1,0] neg_lo:[0,1] neg_hi:[0,1]
	v_pk_add_f32 v[90:91], v[90:91], v[96:97] op_sel_hi:[1,0] neg_lo:[0,1] neg_hi:[0,1]
	v_pk_add_f32 v[92:93], v[92:93], v[96:97] op_sel_hi:[1,0] neg_lo:[0,1] neg_hi:[0,1]
	v_sub_f32_e32 v79, v79, v96
	v_sub_f32_e32 v78, v78, v96
	v_sub_f32_e32 v77, v77, v96
	v_sub_f32_e32 v76, v76, v96
	v_sub_f32_e32 v75, v75, v96
	v_sub_f32_e32 v74, v74, v96
	v_sub_f32_e32 v73, v73, v96
	v_sub_f32_e32 v72, v72, v96
	v_sub_f32_e32 v71, v71, v96
	v_sub_f32_e32 v70, v70, v96
	v_sub_f32_e32 v69, v69, v96
	v_sub_f32_e32 v68, v68, v96
	v_sub_f32_e32 v67, v67, v96
	v_sub_f32_e32 v66, v66, v96
	v_sub_f32_e32 v65, v65, v96
	v_sub_f32_e32 v64, v64, v96
	v_pk_add_f32 v[94:95], v[94:95], v[96:97] op_sel_hi:[1,0] neg_lo:[0,1] neg_hi:[0,1]
	v_pk_mul_f32 v[62:63], v[62:63], v[98:99] op_sel_hi:[1,0]
	v_pk_mul_f32 v[60:61], v[60:61], v[98:99] op_sel_hi:[1,0]
	v_pk_mul_f32 v[58:59], v[58:59], v[98:99] op_sel_hi:[1,0]
	v_pk_mul_f32 v[56:57], v[56:57], v[98:99] op_sel_hi:[1,0]
	v_pk_mul_f32 v[54:55], v[54:55], v[98:99] op_sel_hi:[1,0]
	v_pk_mul_f32 v[52:53], v[52:53], v[98:99] op_sel_hi:[1,0]
	v_pk_mul_f32 v[50:51], v[50:51], v[98:99] op_sel_hi:[1,0]
	v_pk_mul_f32 v[48:49], v[48:49], v[98:99] op_sel_hi:[1,0]
	v_pk_mul_f32 v[46:47], v[46:47], v[98:99] op_sel_hi:[1,0]
	v_pk_mul_f32 v[44:45], v[44:45], v[98:99] op_sel_hi:[1,0]
	v_pk_mul_f32 v[42:43], v[42:43], v[98:99] op_sel_hi:[1,0]
	v_pk_mul_f32 v[40:41], v[40:41], v[98:99] op_sel_hi:[1,0]
	v_pk_mul_f32 v[38:39], v[38:39], v[98:99] op_sel_hi:[1,0]
	v_pk_mul_f32 v[36:37], v[36:37], v[98:99] op_sel_hi:[1,0]
	v_pk_mul_f32 v[34:35], v[34:35], v[98:99] op_sel_hi:[1,0]
	v_pk_mul_f32 v[32:33], v[32:33], v[98:99] op_sel_hi:[1,0]
	v_pk_mul_f32 v[30:31], v[30:31], v[98:99] op_sel_hi:[1,0]
	v_pk_mul_f32 v[28:29], v[28:29], v[98:99] op_sel_hi:[1,0]
	v_pk_mul_f32 v[26:27], v[26:27], v[98:99] op_sel_hi:[1,0]
	v_pk_mul_f32 v[24:25], v[24:25], v[98:99] op_sel_hi:[1,0]
	v_pk_mul_f32 v[22:23], v[22:23], v[98:99] op_sel_hi:[1,0]
	v_pk_mul_f32 v[20:21], v[20:21], v[98:99] op_sel_hi:[1,0]
	v_pk_mul_f32 v[18:19], v[18:19], v[98:99] op_sel_hi:[1,0]
	v_pk_mul_f32 v[16:17], v[16:17], v[98:99] op_sel_hi:[1,0]
	v_pk_mul_f32 v[14:15], v[14:15], v[98:99] op_sel_hi:[1,0]
	v_pk_mul_f32 v[12:13], v[12:13], v[98:99] op_sel_hi:[1,0]
	v_pk_mul_f32 v[10:11], v[10:11], v[98:99] op_sel_hi:[1,0]
	v_pk_mul_f32 v[8:9], v[8:9], v[98:99] op_sel_hi:[1,0]
	v_pk_mul_f32 v[6:7], v[6:7], v[98:99] op_sel_hi:[1,0]
	v_pk_mul_f32 v[4:5], v[4:5], v[98:99] op_sel_hi:[1,0]
	v_pk_mul_f32 v[2:3], v[2:3], v[98:99] op_sel_hi:[1,0]
	v_pk_mul_f32 v[0:1], v[0:1], v[98:99] op_sel_hi:[1,0]
.LBB0_867:
	v_exp_f32_e32 v113, v80
	v_exp_f32_e32 v122, v81
	v_exp_f32_e32 v123, v82
	v_mfma_f32_32x32x16_bf16 v[96:111], v[252:255], v[144:147], v[64:79]
	ds_read_b128 v[248:251], v220 offset:32768
	v_exp_f32_e32 v124, v83
	v_exp_f32_e32 v125, v84
	v_exp_f32_e32 v126, v85
	v_exp_f32_e32 v127, v86
	v_exp_f32_e32 v230, v87
	v_exp_f32_e32 v88, v88
	v_exp_f32_e32 v89, v89
	v_mfma_f32_32x32x16_bf16 v[96:111], v[176:179], v[156:159], v[96:111]
	ds_read_b128 v[252:255], v221 offset:32768
	v_exp_f32_e32 v90, v90
	v_exp_f32_e32 v91, v91
	v_exp_f32_e32 v92, v92
	v_exp_f32_e32 v93, v93
	v_exp_f32_e32 v94, v94
	v_exp_f32_e32 v95, v95
	v_mfma_f32_32x32x16_bf16 v[96:111], v[180:183], v[168:171], v[96:111]
	ds_read_b128 v[176:179], v206 offset:16384
	v_mfma_f32_32x32x16_bf16 v[96:111], v[236:239], v[172:175], v[96:111]
	ds_read_b128 v[180:183], v208 offset:16384
	v_mfma_f32_32x32x16_bf16 v[96:111], v[240:243], v[164:167], v[96:111]
	ds_read_b128 v[236:239], v210 offset:16384
	s_waitcnt lgkmcnt(3)
	v_mfma_f32_32x32x16_bf16 v[96:111], v[244:247], v[160:163], v[96:111]
	ds_read_b128 v[240:243], v212 offset:16384
	v_mfma_f32_32x32x16_bf16 v[96:111], v[248:251], v[152:155], v[96:111]
	ds_read_b128 v[244:247], v227 offset:16384
	v_mfma_f32_32x32x16_bf16 v[96:111], v[252:255], v[148:151], v[96:111]
	ds_read_b128 v[248:251], v227 offset:20480
	s_waitcnt lgkmcnt(3)
	v_mfma_f32_32x32x16_bf16 v[96:111], v[176:179], v[140:143], v[96:111]
	ds_read_b128 v[252:255], v227 offset:24576
	v_mfma_f32_32x32x16_bf16 v[96:111], v[180:183], v[136:139], v[96:111]
	ds_read_b128 v[176:179], v227 offset:28672
	v_mfma_f32_32x32x16_bf16 v[96:111], v[236:239], v[132:135], v[96:111]
	ds_read_b128 v[180:183], v228 offset:20480
	v_cvt_pk_bf16_f32 v114, v113, v122
	v_cvt_pk_bf16_f32 v115, v123, v124
	v_cvt_pk_bf16_f32 v116, v125, v126
	v_cvt_pk_bf16_f32 v117, v127, v230
	s_waitcnt lgkmcnt(3)
	v_mfma_f32_32x32x16_bf16 v[96:111], v[240:243], v[128:131], v[96:111]
	ds_read_b128 v[236:239], v228 offset:16384
	v_add_f32_e32 v118, 0, v113
	v_add_f32_e32 v113, v122, v118
	v_add_f32_e32 v113, v123, v113
	v_mfma_f32_32x32x16_bf16 v[48:63], v[244:247], v[114:117], v[48:63]
	ds_read_b128 v[240:243], v228 offset:24576
	v_add_f32_e32 v80, v124, v113
	v_add_f32_e32 v80, v125, v80
	v_add_f32_e32 v80, v126, v80
	v_add_f32_e32 v113, v127, v80
	v_mfma_f32_32x32x16_bf16 v[32:47], v[248:251], v[114:117], v[32:47]
	ds_read_b128 v[244:247], v228 offset:28672
	v_add_f32_e32 v84, v230, v113
	v_add_f32_e32 v84, v88, v84
	v_add_f32_e32 v113, v89, v84
	s_waitcnt lgkmcnt(3)
	v_mfma_f32_32x32x16_bf16 v[16:31], v[252:255], v[114:117], v[16:31]
	ds_read_b128 v[248:251], v214 offset:40960
	v_add_f32_e32 v80, v90, v113
	v_add_f32_e32 v80, v91, v80
	v_add_f32_e32 v80, v92, v80
	v_add_f32_e32 v113, v93, v80
	v_add_f32_e32 v113, v94, v113
	v_mfma_f32_32x32x16_bf16 v[0:15], v[176:179], v[114:117], v[0:15]
	ds_read_b128 v[252:255], v215 offset:40960
	v_cvt_pk_bf16_f32 v84, v88, v89
	v_cvt_pk_bf16_f32 v85, v90, v91
	v_cvt_pk_bf16_f32 v86, v92, v93
	v_max_f32_e32 v92, v96, v97
	v_max3_f32 v92, v92, v98, v99
	v_max3_f32 v92, v92, v100, v101
	v_cvt_pk_bf16_f32 v87, v94, v95
	v_max3_f32 v92, v92, v102, v103
	v_add_f32_e32 v94, v95, v113
	v_mfma_f32_32x32x16_bf16 v[32:47], v[180:183], v[84:87], v[32:47]
	ds_read_b128 v[176:179], v216 offset:40960
	v_max3_f32 v88, v92, v104, v105
	v_max3_f32 v88, v88, v106, v107
	v_max3_f32 v88, v88, v108, v109
	v_max3_f32 v92, v88, v110, v111
	ds_bpermute_b32 v93, v229, v92
	v_add_f32_e32 v112, v112, v94
	s_waitcnt lgkmcnt(4)
	v_mfma_f32_32x32x16_bf16 v[48:63], v[236:239], v[84:87], v[48:63]
	ds_read_b128 v[180:183], v217 offset:40960
	s_waitcnt vmcnt(0)
	s_barrier
	v_mfma_f32_32x32x16_bf16 v[16:31], v[240:243], v[84:87], v[16:31]
	ds_read_b128 v[236:239], v218 offset:40960
	s_waitcnt lgkmcnt(2)
	v_max_f32_e32 v80, v92, v93
	v_cmp_lt_f32_e32 vcc, 0, v80
	v_mfma_f32_32x32x16_bf16 v[0:15], v[244:247], v[84:87], v[0:15]
	ds_read_b128 v[240:243], v219 offset:40960
	s_cbranch_vccz .LBB0_869
	v_max_f32_e32 v80, v80, v80
	v_max_f32_e32 v80, 0, v80
	v_exp_f32_e64 v82, -v80
	v_pk_add_f32 v[96:97], v[96:97], v[80:81] op_sel_hi:[1,0] neg_lo:[0,1] neg_hi:[0,1]
	v_pk_add_f32 v[98:99], v[98:99], v[80:81] op_sel_hi:[1,0] neg_lo:[0,1] neg_hi:[0,1]
	v_pk_add_f32 v[100:101], v[100:101], v[80:81] op_sel_hi:[1,0] neg_lo:[0,1] neg_hi:[0,1]
	v_mul_f32_e32 v112, v112, v82
	v_pk_add_f32 v[102:103], v[102:103], v[80:81] op_sel_hi:[1,0] neg_lo:[0,1] neg_hi:[0,1]
	v_pk_add_f32 v[104:105], v[104:105], v[80:81] op_sel_hi:[1,0] neg_lo:[0,1] neg_hi:[0,1]
	v_pk_add_f32 v[106:107], v[106:107], v[80:81] op_sel_hi:[1,0] neg_lo:[0,1] neg_hi:[0,1]
	v_pk_add_f32 v[108:109], v[108:109], v[80:81] op_sel_hi:[1,0] neg_lo:[0,1] neg_hi:[0,1]
	v_sub_f32_e32 v79, v79, v80
	v_sub_f32_e32 v78, v78, v80
	v_sub_f32_e32 v77, v77, v80
	v_sub_f32_e32 v76, v76, v80
	v_sub_f32_e32 v75, v75, v80
	v_sub_f32_e32 v74, v74, v80
	v_sub_f32_e32 v73, v73, v80
	v_sub_f32_e32 v72, v72, v80
	v_sub_f32_e32 v71, v71, v80
	v_sub_f32_e32 v70, v70, v80
	v_sub_f32_e32 v69, v69, v80
	v_sub_f32_e32 v68, v68, v80
	v_sub_f32_e32 v67, v67, v80
	v_sub_f32_e32 v66, v66, v80
	v_sub_f32_e32 v65, v65, v80
	v_sub_f32_e32 v64, v64, v80
	v_pk_add_f32 v[110:111], v[110:111], v[80:81] op_sel_hi:[1,0] neg_lo:[0,1] neg_hi:[0,1]
	v_pk_mul_f32 v[62:63], v[62:63], v[82:83] op_sel_hi:[1,0]
	v_pk_mul_f32 v[60:61], v[60:61], v[82:83] op_sel_hi:[1,0]
	v_pk_mul_f32 v[58:59], v[58:59], v[82:83] op_sel_hi:[1,0]
	v_pk_mul_f32 v[56:57], v[56:57], v[82:83] op_sel_hi:[1,0]
	v_pk_mul_f32 v[54:55], v[54:55], v[82:83] op_sel_hi:[1,0]
	v_pk_mul_f32 v[52:53], v[52:53], v[82:83] op_sel_hi:[1,0]
	v_pk_mul_f32 v[50:51], v[50:51], v[82:83] op_sel_hi:[1,0]
	v_pk_mul_f32 v[48:49], v[48:49], v[82:83] op_sel_hi:[1,0]
	v_pk_mul_f32 v[46:47], v[46:47], v[82:83] op_sel_hi:[1,0]
	v_pk_mul_f32 v[44:45], v[44:45], v[82:83] op_sel_hi:[1,0]
	v_pk_mul_f32 v[42:43], v[42:43], v[82:83] op_sel_hi:[1,0]
	v_pk_mul_f32 v[40:41], v[40:41], v[82:83] op_sel_hi:[1,0]
	v_pk_mul_f32 v[38:39], v[38:39], v[82:83] op_sel_hi:[1,0]
	v_pk_mul_f32 v[36:37], v[36:37], v[82:83] op_sel_hi:[1,0]
	v_pk_mul_f32 v[34:35], v[34:35], v[82:83] op_sel_hi:[1,0]
	v_pk_mul_f32 v[32:33], v[32:33], v[82:83] op_sel_hi:[1,0]
	v_pk_mul_f32 v[30:31], v[30:31], v[82:83] op_sel_hi:[1,0]
	v_pk_mul_f32 v[28:29], v[28:29], v[82:83] op_sel_hi:[1,0]
	v_pk_mul_f32 v[26:27], v[26:27], v[82:83] op_sel_hi:[1,0]
	v_pk_mul_f32 v[24:25], v[24:25], v[82:83] op_sel_hi:[1,0]
	v_pk_mul_f32 v[22:23], v[22:23], v[82:83] op_sel_hi:[1,0]
	v_pk_mul_f32 v[20:21], v[20:21], v[82:83] op_sel_hi:[1,0]
	v_pk_mul_f32 v[18:19], v[18:19], v[82:83] op_sel_hi:[1,0]
	v_pk_mul_f32 v[16:17], v[16:17], v[82:83] op_sel_hi:[1,0]
	v_pk_mul_f32 v[14:15], v[14:15], v[82:83] op_sel_hi:[1,0]
	v_pk_mul_f32 v[12:13], v[12:13], v[82:83] op_sel_hi:[1,0]
	v_pk_mul_f32 v[10:11], v[10:11], v[82:83] op_sel_hi:[1,0]
	v_pk_mul_f32 v[8:9], v[8:9], v[82:83] op_sel_hi:[1,0]
	v_pk_mul_f32 v[6:7], v[6:7], v[82:83] op_sel_hi:[1,0]
	v_pk_mul_f32 v[4:5], v[4:5], v[82:83] op_sel_hi:[1,0]
	v_pk_mul_f32 v[2:3], v[2:3], v[82:83] op_sel_hi:[1,0]
	v_pk_mul_f32 v[0:1], v[0:1], v[82:83] op_sel_hi:[1,0]
.LBB0_869:
	v_exp_f32_e32 v96, v96
	v_exp_f32_e32 v97, v97
	v_exp_f32_e32 v98, v98
	v_mfma_f32_32x32x16_bf16 v[80:95], v[248:251], v[144:147], v[64:79]
	ds_read_b128 v[244:247], v220 offset:40960
	v_exp_f32_e32 v99, v99
	v_exp_f32_e32 v100, v100
	v_exp_f32_e32 v101, v101
	v_exp_f32_e32 v102, v102
	v_exp_f32_e32 v103, v103
	v_cvt_pk_bf16_f32 v122, v96, v97
	v_cvt_pk_bf16_f32 v123, v98, v99
	v_mfma_f32_32x32x16_bf16 v[80:95], v[252:255], v[156:159], v[80:95]
	ds_read_b128 v[248:251], v221 offset:40960
	s_add_i32 s4, s8, 4
	s_cmp_ge_u32 s4, s9
	s_cbranch_scc1 .Lmla_dma_skip_t2
	s_mov_b32 m0, s46
	s_cmp_lg_u64 s[24:25], 0
	s_cselect_b64 s[4:5], s[100:101], s[98:99]
	global_load_lds_dwordx4 v190, s[4:5]
	s_mov_b32 m0, s47
	s_cmp_lg_u64 s[26:27], 0
	s_cselect_b64 s[4:5], s[100:101], s[98:99]
	global_load_lds_dwordx4 v192, s[4:5]
	s_mov_b32 m0, s48
	s_cmp_lg_u64 s[28:29], 0
	s_cselect_b64 s[4:5], s[100:101], s[98:99]
	global_load_lds_dwordx4 v194, s[4:5]
	s_mov_b32 m0, s49
	s_cmp_lg_u64 s[30:31], 0
	s_cselect_b64 s[4:5], s[100:101], s[98:99]
	global_load_lds_dwordx4 v196, s[4:5]
	s_mov_b32 m0, s50
	s_cmp_lg_u64 s[6:7], 0
	s_cselect_b64 s[4:5], s[100:101], s[98:99]
	global_load_lds_dwordx4 v198, s[4:5]
	s_add_u32 s98, s98, 0x6000
	s_addc_u32 s99, s99, 0
	s_add_u32 s100, s100, 0x80
	s_addc_u32 s101, s101, 0
.Lmla_dma_skip_t2:
	v_cvt_pk_bf16_f32 v124, v100, v101
	v_cvt_pk_bf16_f32 v125, v102, v103
	v_exp_f32_e32 v104, v104
	v_exp_f32_e32 v105, v105
	v_exp_f32_e32 v106, v106
	v_exp_f32_e32 v107, v107
	v_mfma_f32_32x32x16_bf16 v[80:95], v[176:179], v[168:171], v[80:95]
	ds_read_b128 v[252:255], v206 offset:20480
	v_exp_f32_e32 v108, v108
	v_exp_f32_e32 v109, v109
	v_exp_f32_e32 v110, v110
	v_exp_f32_e32 v111, v111
	s_add_i32 s4, s8, 4
	s_cmp_ge_u32 s4, s9
	s_waitcnt lgkmcnt(3)
	v_mfma_f32_32x32x16_bf16 v[80:95], v[180:183], v[172:175], v[80:95]
	ds_read_b128 v[176:179], v208 offset:20480
	v_mfma_f32_32x32x16_bf16 v[80:95], v[236:239], v[164:167], v[80:95]
	ds_read_b128 v[180:183], v210 offset:20480
	v_mfma_f32_32x32x16_bf16 v[80:95], v[240:243], v[160:163], v[80:95]
	ds_read_b128 v[236:239], v212 offset:20480
	s_waitcnt lgkmcnt(3)
	v_mfma_f32_32x32x16_bf16 v[80:95], v[244:247], v[152:155], v[80:95]
	ds_read_b128 v[240:243], v225 offset:32768
	v_mfma_f32_32x32x16_bf16 v[80:95], v[248:251], v[148:151], v[80:95]
	ds_read_b128 v[244:247], v225 offset:36864
	v_mfma_f32_32x32x16_bf16 v[80:95], v[252:255], v[140:143], v[80:95]
	ds_read_b128 v[248:251], v225 offset:40960
	s_waitcnt lgkmcnt(3)
	v_mfma_f32_32x32x16_bf16 v[80:95], v[176:179], v[136:139], v[80:95]
	ds_read_b128 v[252:255], v225 offset:45056
	v_mfma_f32_32x32x16_bf16 v[80:95], v[180:183], v[132:135], v[80:95]
	ds_read_b128 v[176:179], v226 offset:32768
	v_mfma_f32_32x32x16_bf16 v[80:95], v[236:239], v[128:131], v[80:95]
	ds_read_b128 v[180:183], v226 offset:36864
	s_waitcnt lgkmcnt(3)
	v_mfma_f32_32x32x16_bf16 v[48:63], v[240:243], v[122:125], v[48:63]
	ds_read_b128 v[236:239], v226 offset:40960
	v_add_f32_e32 v96, 0, v96
	v_add_f32_e32 v96, v97, v96
	v_add_f32_e32 v96, v98, v96
	v_add_f32_e32 v96, v99, v96
	v_add_f32_e32 v96, v100, v96
	v_add_f32_e32 v96, v101, v96
	v_add_f32_e32 v96, v102, v96
	v_add_f32_e32 v96, v103, v96
	v_add_f32_e32 v96, v104, v96
	v_max_f32_e32 v113, v80, v81
	v_max3_f32 v113, v113, v82, v83
	v_max3_f32 v113, v113, v84, v85
	v_max3_f32 v113, v113, v86, v87
	v_max3_f32 v113, v113, v88, v89
	v_mfma_f32_32x32x16_bf16 v[32:47], v[244:247], v[122:125], v[32:47]
	ds_read_b128 v[240:243], v226 offset:45056
	v_max3_f32 v113, v113, v90, v91
	v_max3_f32 v113, v113, v92, v93
	v_max3_f32 v113, v113, v94, v95
	v_mfma_f32_32x32x16_bf16 v[16:31], v[248:251], v[122:125], v[16:31]
	ds_read_b128 v[244:247], v214
	s_waitcnt lgkmcnt(3)
	v_mfma_f32_32x32x16_bf16 v[0:15], v[252:255], v[122:125], v[0:15]
	ds_read_b128 v[248:251], v215
	v_cvt_pk_bf16_f32 v118, v104, v105
	v_cvt_pk_bf16_f32 v119, v106, v107
	v_cvt_pk_bf16_f32 v120, v108, v109
	v_cvt_pk_bf16_f32 v121, v110, v111
	s_nop 0
	s_nop 0
	v_mfma_f32_32x32x16_bf16 v[48:63], v[176:179], v[118:121], v[48:63]
	ds_read_b128 v[252:255], v216
	v_mfma_f32_32x32x16_bf16 v[32:47], v[180:183], v[118:121], v[32:47]
	ds_read_b128 v[176:179], v217
	s_waitcnt lgkmcnt(3)
	v_mfma_f32_32x32x16_bf16 v[16:31], v[236:239], v[118:121], v[16:31]
	ds_read_b128 v[180:183], v218
	ds_bpermute_b32 v114, v229, v113
	v_mfma_f32_32x32x16_bf16 v[0:15], v[240:243], v[118:121], v[0:15]
	ds_read_b128 v[236:239], v219

.LBB0_873:
	v_exp_f32_e32 v113, v80
	v_exp_f32_e32 v126, v85
	v_exp_f32_e32 v127, v86
	v_mfma_f32_32x32x16_bf16 v[96:111], v[244:247], v[144:147], v[64:79]
	ds_read_b128 v[240:243], v220
	v_add_f32_e32 v231, 0, v113
	v_exp_f32_e32 v230, v87
	v_exp_f32_e32 v88, v88
	v_exp_f32_e32 v89, v89
	v_exp_f32_e32 v90, v90
	v_exp_f32_e32 v91, v91
	v_exp_f32_e32 v92, v92
	v_mfma_f32_32x32x16_bf16 v[96:111], v[248:251], v[156:159], v[96:111]
	ds_read_b128 v[244:247], v221
	v_exp_f32_e32 v93, v93
	s_add_u32 s62, s62, 0x180
	s_addc_u32 s61, s61, 0
	s_add_u32 s60, s60, 0x12000
	s_addc_u32 s59, s59, 0
	s_add_i32 s4, s16, 3
	v_mfma_f32_32x32x16_bf16 v[96:111], v[252:255], v[168:171], v[96:111]
	ds_read_b128 v[248:251], v206
	s_cmp_le_u32 s4, s9
	v_mfma_f32_32x32x16_bf16 v[96:111], v[176:179], v[172:175], v[96:111]
	ds_read_b128 v[252:255], v208
	v_mfma_f32_32x32x16_bf16 v[96:111], v[180:183], v[164:167], v[96:111]
	ds_read_b128 v[176:179], v210
	s_waitcnt lgkmcnt(3)
	v_mfma_f32_32x32x16_bf16 v[96:111], v[236:239], v[160:163], v[96:111]
	ds_read_b128 v[180:183], v212
	v_mfma_f32_32x32x16_bf16 v[96:111], v[240:243], v[152:155], v[96:111]
	ds_read_b128 v[236:239], v227 offset:32768
	v_mfma_f32_32x32x16_bf16 v[96:111], v[244:247], v[148:151], v[96:111]
	ds_read_b128 v[240:243], v227 offset:36864
	s_waitcnt lgkmcnt(3)
	v_mfma_f32_32x32x16_bf16 v[96:111], v[248:251], v[140:143], v[96:111]
	ds_read_b128 v[244:247], v227 offset:40960
	v_mfma_f32_32x32x16_bf16 v[96:111], v[252:255], v[136:139], v[96:111]
	ds_read_b128 v[248:251], v227 offset:45056
	v_exp_f32_e32 v118, v81
	v_exp_f32_e32 v119, v82
	v_exp_f32_e32 v120, v83
	v_exp_f32_e32 v121, v84
	v_mfma_f32_32x32x16_bf16 v[96:111], v[176:179], v[132:135], v[96:111]
	ds_read_b128 v[252:255], v228 offset:36864
	v_cvt_pk_bf16_f32 v114, v113, v118
	v_add_f32_e32 v113, v118, v231
	v_add_f32_e32 v113, v119, v113
	v_add_f32_e32 v113, v120, v113
	v_add_f32_e32 v113, v121, v113
	v_cvt_pk_bf16_f32 v115, v119, v120
	v_cvt_pk_bf16_f32 v116, v121, v126
	v_cvt_pk_bf16_f32 v117, v127, v230
	v_add_f32_e32 v113, v126, v113
	s_waitcnt lgkmcnt(3)
	v_mfma_f32_32x32x16_bf16 v[96:111], v[180:183], v[128:131], v[96:111]
	ds_read_b128 v[176:179], v228 offset:32768
	v_exp_f32_e32 v118, v94
	v_exp_f32_e32 v119, v95
	v_mfma_f32_32x32x16_bf16 v[48:63], v[236:239], v[114:117], v[48:63]
	ds_read_b128 v[180:183], v228 offset:40960
	v_add_f32_e32 v80, v127, v113
	v_add_f32_e32 v80, v230, v80
	v_add_f32_e32 v113, v88, v80
	v_cvt_pk_bf16_f32 v88, v88, v89
	v_mfma_f32_32x32x16_bf16 v[32:47], v[240:243], v[114:117], v[32:47]
	ds_read_b128 v[236:239], v228 offset:45056
	v_add_f32_e32 v84, v89, v113
	v_add_f32_e32 v84, v90, v84
	v_add_f32_e32 v84, v91, v84
	v_add_f32_e32 v113, v92, v84
	v_add_f32_e32 v113, v93, v113
	v_cvt_pk_bf16_f32 v89, v90, v91
	s_waitcnt lgkmcnt(3)
	v_mfma_f32_32x32x16_bf16 v[16:31], v[244:247], v[114:117], v[16:31]
	v_cvt_pk_bf16_f32 v90, v92, v93
	v_cvt_pk_bf16_f32 v91, v118, v119
	v_mfma_f32_32x32x16_bf16 v[0:15], v[248:251], v[114:117], v[0:15]
	v_max_f32_e32 v115, v96, v96
	v_max_f32_e32 v114, v115, v97
	v_max3_f32 v114, v114, v98, v99
	v_mfma_f32_32x32x16_bf16 v[32:47], v[252:255], v[88:91], v[32:47]
	s_waitcnt vmcnt(0)
	s_barrier
	s_waitcnt lgkmcnt(2)
	v_mfma_f32_32x32x16_bf16 v[48:63], v[176:179], v[88:91], v[48:63]
	v_max3_f32 v80, v114, v100, v101
	v_max3_f32 v80, v80, v102, v103
	v_max3_f32 v80, v80, v104, v105
	v_max3_f32 v80, v80, v106, v107
	v_max3_f32 v80, v80, v108, v109
	v_max3_f32 v80, v80, v110, v111
	ds_bpermute_b32 v81, v229, v80
	s_waitcnt lgkmcnt(2)
	v_mfma_f32_32x32x16_bf16 v[16:31], v[180:183], v[88:91], v[16:31]
	v_add_f32_e32 v82, v118, v113
	v_add_f32_e32 v82, v119, v82
	v_add_f32_e32 v230, v112, v82
	s_waitcnt lgkmcnt(0)
	v_max_f32_e32 v81, v81, v81
	v_max_f32_e32 v82, v80, v81
	v_mfma_f32_32x32x16_bf16 v[0:15], v[236:239], v[88:91], v[0:15]
	s_cbranch_scc0 .LBB0_875
	s_mov_b32 s8, s16
	v_cmp_lt_f32_e32 vcc, 0, v82
	s_cbranch_vccnz .LBB0_858
	s_branch .LBB0_859
